# finalize: prompt-row sums moved to otherwise idle blocks 128..159 (overlaps the sample-row loop)
# baseline (speedup 1.0000x reference)
.LBB0_59:
	v_readlane_b32 s1, v240, 23
	s_cmp_eq_u32 s1, 6
	s_cselect_b32 s0, 1, 2
	s_cmp_lg_u32 s1, 2
	s_cselect_b32 s0, s0, 0
	s_add_i32 s0, s0, s14
	s_mul_hi_i32 s1, s0, 0x11000
	s_mul_i32 s0, s0, 0x11000
	v_readlane_b32 s6, v243, 17
	s_add_u32 s6, s6, s0
	v_readlane_b32 s0, v243, 18
	s_addc_u32 s7, s0, s1
	v_mov_b32_e32 v2, v147
	v_readlane_b32 s0, v241, 32
	s_sub_i32 s0, s0, 0x10000
	s_nop 1
	v_add_u32_e32 v0, s0, v2
	s_movk_i32 s0, 0x4000
	v_cmp_gt_u32_e32 vcc, s0, v0
	s_and_saveexec_b64 s[0:1], vcc
	v_readlane_b32 s10, v243, 21
	v_readlane_b32 s11, v243, 22
	v_readlane_b32 s12, v243, 23
	s_cbranch_execz .LBB0_62
	s_mov_b64 s[8:9], 0
